# GU epilogue: per-lane rstd cached in spare LDS across units with equal row tile (skips 8 global loads + reduction on hit); on top of K-loop peel
# speedup vs baseline: 1.0438x; 1.0201x over previous
; template <class Epi, class Sched, bool ALIGN_EPI = false, bool SP2 = false>
; __device__ __forceinline__ void gemm_phase(PG8_LAS unsigned char* lds, const Gemm g, const Sched& S, const Epi& E) {
;     const int tid = opaque_tid(), wid = __builtin_amdgcn_readfirstlane(tid >> 6), lane = tid & 63, wr = wid >> 2, wc = wid & 3, fr = lane & 15, fq = lane >> 4;
;     const int K = g.K, nt = K / BK;
;     unsigned voffA[2], voffB[2];
; #pragma unroll
;     for (int i = 0; i < 2; ++i) { int R, C; stage_rc(tid * 16 + i * 8192, R, C); const int Rb = Epi::PERM ? ((R & ~31) + perm32(R & 31)) : R;
;         voffA[i] = (unsigned)(R * K + C) * 2u; voffB[i] = (unsigned)(Rb * K + C) * 2u; }
;     const size_t kstep = (size_t)(BK * 2);
;     const size_t hstep = (size_t)HALF * K * 2;
;     const size_t tstep = 2 * hstep;
;     const unsigned ldsw = (unsigned)wid * 1024u;
;     const int aoff = lds_byte(wr * 64 + fr, fq * 8), boff = lds_byte(wc * 32 + fr, fq * 8);
;     ...
;     Unit cur, nxt; int ui = 0;
;     if (!S.next(0, cur)) return;
;     f32x4 acc[2][2][4][2];
; #pragma unroll
;     for (int a = 0; a < 2; ++a)
; #pragma unroll
;         for (int b = 0; b < 2; ++b)
; #pragma unroll
;             for (int m = 0; m < 4; ++m)
; #pragma unroll
;                 for (int n = 0; n < 2; ++n) acc[a][b][m][n] = (f32x4){0.f, 0.f, 0.f, 0.f};
;     bf16x8 At[4][2], B0[2][2], B1[2][2];
;     const char* cA = (const char*)g.A + (size_t)cur.pm * tstep; const char* cB = (const char*)g.Bt + (size_t)cur.pn * tstep;
;     S.a_ready(cur);
;     if constexpr (SP2) {
;         PG8_STAGE(PG8_SB(0, 0), cB, voffB); PG8_STAGE(PG8_SB(0, 1), cB + hstep, voffB); PG8_STAGE(PG8_SA(0, 0), cA, voffA); PG8_STAGE(PG8_SA(0, 1), cA + hstep, voffA);
;         if (wr == 1) PG8_BAR;
;         PG8_WAIT_V(2); PG8_BAR;
;         PG8_STAGE(PG8_SB(1, 0), cB + kstep, voffB); PG8_STAGE(PG8_SA(1, 0), cA + kstep, voffA); PG8_STAGE(PG8_SB(1, 1), cB + hstep + kstep, voffB);
;         PG8_WAIT_V(6); PG8_BAR;
;     } else {
;         PG8_STAGE(PG8_SB(0, 0), cB, voffB); PG8_STAGE(PG8_SA(0, 0), cA, voffA); PG8_STAGE(PG8_SB(0, 1), cB + hstep, voffB); PG8_STAGE(PG8_SA(0, 1), cA + hstep, voffA);
;         if (wr == 1) PG8_BAR;
;         PG8_WAIT_V(4); PG8_BAR;
;         PG8_STAGE(PG8_SB(1, 0), cB + kstep, voffB); PG8_STAGE(PG8_SA(1, 0), cA + kstep, voffA); PG8_STAGE(PG8_SB(1, 1), cB + hstep + kstep, voffB);
.LBB0_177:
	s_movk_i32 s0, 0x400
	s_movk_i32 s1, 0x1600
	s_ashr_i32 s11, s1, 31
	s_lshr_b32 s11, s11, 24
	s_add_i32 s1, s1, s11
	s_ashr_i32 s28, s1, 8
	s_lshl_b32 s42, s28, 7
	v_mov_b32_e32 v12, v238
	s_cmp_ge_i32 s2, s42
	v_readfirstlane_b32 s18, v12
	s_cbranch_scc1 .LBB0_176
	v_lshlrev_b32_e32 v0, 2, v238
	v_add_u32_e32 v0, 0x20000, v0
	v_mov_b32_e32 v1, -1
	ds_write_b32 v0, v1
	v_lshlrev_b32_e32 v0, 4, v12
	v_add_u32_e32 v1, 0x2000, v0
	v_ashrrev_i32_e32 v2, 31, v1
	v_lshrrev_b32_e32 v2, 22, v2
	v_add_u32_e32 v2, v1, v2
	v_ashrrev_i32_e32 v2, 10, v2
	v_mul_i32_i24_e32 v3, 0x400, v2
	v_sub_u32_e32 v1, v1, v3
	v_lshrrev_b32_e32 v3, 4, v1
	v_bitop3_b32 v1, v3, v1, 32 bitop3:0x6c
	v_ashrrev_i32_e32 v3, 31, v1
	v_lshrrev_b32_e32 v3, 26, v3
	v_add_u32_e32 v3, v1, v3
	v_lshlrev_b32_e32 v5, 3, v2
	v_ashrrev_i32_e32 v4, 6, v3
	v_and_b32_e32 v5, -16, v5
	v_lshlrev_b32_e32 v2, 5, v2
	v_add_u32_e32 v5, v4, v5
	v_and_b32_e32 v13, 32, v2
	v_and_b32_e32 v2, 0xc0, v3
	v_and_b32_e32 v4, 3, v4
	s_mov_b32 s10, 0x7fffffe0
	v_lshrrev_b32_e32 v6, 2, v5
	v_lshlrev_b32_e32 v7, 1, v5
	v_sub_u32_e32 v1, v1, v2
	v_and_or_b32 v4, v5, s10, v4
	v_and_b32_e32 v6, 4, v6
	v_and_b32_e32 v7, 24, v7
	v_ashrrev_i16_sdwa v1, v241, sext(v1) dst_sel:DWORD dst_unused:UNUSED_PAD src0_sel:DWORD src1_sel:BYTE_0
	v_or3_b32 v4, v4, v6, v7
	v_bfe_i32 v14, v1, 0, 16
	v_mul_lo_u32 v4, v4, s0
	v_add_u32_e32 v1, v13, v14
	v_mul_lo_u32 v15, v5, s0
	s_waitcnt vmcnt(0)
	v_add_lshl_u32 v128, v4, v1, 1
	v_add_lshl_u32 v130, v1, v15, 1
	v_bfe_i32 v1, v12, 27, 1
	v_lshrrev_b32_e32 v1, 22, v1
	v_add_u32_e32 v1, v0, v1
	v_and_b32_e32 v1, 0xfffffc00, v1
	v_sub_u32_e32 v0, v0, v1
	v_ashrrev_i32_e32 v2, 31, v12
	v_lshrrev_b32_e32 v1, 4, v0
	v_lshrrev_b32_e32 v2, 26, v2
	s_ashr_i32 s38, s18, 6
	s_ashr_i32 s1, s0, 31
	v_bitop3_b32 v1, v1, v0, 32 bitop3:0x6c
	v_ashrrev_i32_e32 v0, 31, v0
	v_add_u32_e32 v2, v12, v2
	s_lshl_b32 s36, s28, 4
	s_ashr_i32 s39, s18, 8
	s_lshl_b64 s[44:45], s[0:1], 8
	s_lshl_b64 s[50:51], s[0:1], 9
	s_lshl_b32 s11, s38, 10
	v_lshrrev_b32_e32 v0, 26, v0
	v_ashrrev_i32_e32 v2, 6, v2
	s_or_b32 s37, s36, 1
	v_add_u32_e32 v0, v1, v0
	v_lshlrev_b32_e32 v3, 3, v2
	s_and_b64 s[30:31], s[22:23], exec
	v_ashrrev_i32_e32 v0, 6, v0
	v_and_b32_e32 v3, -16, v3
	s_cselect_b32 s29, s37, s36
	s_lshl_b32 s48, s28, 3
	v_add_u32_e32 v3, v0, v3
	v_and_b32_e32 v4, 3, v0
	v_mul_i32_i24_e32 v0, 64, v0
	s_abs_i32 s58, s48
	v_sub_u32_e32 v0, v1, v0
	v_cvt_f32_u32_e32 v1, s58
	s_mul_i32 s29, s29, s17
	s_sub_i32 s31, 0, s58
	s_add_i32 s29, s29, s16
	v_rcp_iflag_f32_e32 v1, v1
	s_ashr_i32 s30, s29, 31
	s_bfe_i32 s59, s28, 0x1001c
	s_xor_b32 s28, s30, s59
	v_mul_f32_e32 v1, 0x4f7ffffe, v1
	v_cvt_u32_f32_e32 v1, v1
	s_abs_i32 s30, s29
	v_lshrrev_b32_e32 v5, 2, v3
	v_lshlrev_b32_e32 v6, 1, v3
	v_readfirstlane_b32 s60, v1
	s_mul_i32 s31, s31, s60
	s_mul_hi_u32 s31, s60, s31
	s_add_i32 s60, s60, s31
	s_mul_hi_u32 s31, s30, s60
	s_mul_i32 s34, s31, s58
	s_sub_i32 s30, s30, s34
	s_add_i32 s34, s31, 1
	s_sub_i32 s35, s30, s58
	s_cmp_ge_u32 s30, s58
	s_cselect_b32 s31, s34, s31
	s_cselect_b32 s30, s35, s30
	s_add_i32 s34, s31, 1
	s_cmp_ge_u32 s30, s58
	s_cselect_b32 s30, s34, s31
	s_xor_b32 s30, s30, s28
	s_sub_i32 s28, s30, s28
	s_lshl_b32 s30, s28, 3
	s_sub_i32 s31, 0x80, s30
	s_min_i32 s31, s31, 8
	s_abs_i32 s34, s31
	v_cvt_f32_u32_e32 v1, s34
	v_and_or_b32 v4, v3, s10, v4
	v_and_b32_e32 v5, 4, v5
	v_and_b32_e32 v6, 24, v6
	v_lshlrev_b32_e32 v2, 5, v2
	v_ashrrev_i16_sdwa v0, v241, sext(v0) dst_sel:DWORD dst_unused:UNUSED_PAD src0_sel:DWORD src1_sel:BYTE_0
	v_or3_b32 v4, v4, v5, v6
	v_and_b32_e32 v16, 32, v2
	v_bfe_i32 v17, v0, 0, 16
	v_mul_lo_u32 v4, v4, s0
	v_add_u32_e32 v0, v16, v17
	v_mul_lo_u32 v18, v3, s0
	v_add_lshl_u32 v132, v4, v0, 1
	v_add_lshl_u32 v134, v0, v18, 1
	v_rcp_iflag_f32_e32 v0, v1
	s_sub_i32 s43, 0, s34
	s_mul_i32 s28, s28, s48
	s_sub_i32 s28, s29, s28
	v_mul_f32_e32 v0, 0x4f7ffffe, v0
	v_cvt_u32_f32_e32 v0, v0
	s_abs_i32 s35, s28
	s_xor_b32 s29, s28, s31
	s_ashr_i32 s29, s29, 31
	v_readfirstlane_b32 s52, v0
	s_mul_i32 s43, s43, s52
	s_mul_hi_u32 s43, s52, s43
	s_add_i32 s52, s52, s43
	s_mul_hi_u32 s43, s35, s52
	s_mul_i32 s52, s43, s34
	s_sub_i32 s35, s35, s52
	s_add_i32 s52, s43, 1
	s_sub_i32 s53, s35, s34
	s_cmp_ge_u32 s35, s34
	s_cselect_b32 s43, s52, s43
	s_cselect_b32 s35, s53, s35
	s_add_i32 s52, s43, 1
	s_cmp_ge_u32 s35, s34
	s_cselect_b32 s34, s52, s43
	s_xor_b32 s34, s34, s29
	s_sub_i32 s72, s34, s29
	s_mul_i32 s29, s72, s31
	s_sub_i32 s28, s28, s29
	s_add_i32 s73, s28, s30
	s_ashr_i32 s28, s73, 31
	s_mul_i32 s28, s50, s28
	s_mul_hi_u32 s29, s50, s73
	s_add_i32 s30, s29, s28
	s_lshr_b64 s[28:29], s[0:1], 23
	s_mul_i32 s29, s28, s73
	s_add_i32 s31, s30, s29
	s_ashr_i32 s29, s72, 31
	s_mul_i32 s29, s50, s29
	s_mul_hi_u32 s34, s50, s72
	s_add_i32 s29, s34, s29
	s_mul_i32 s28, s28, s72
	s_add_i32 s29, s29, s28
	s_mul_i32 s28, s50, s72
	s_add_u32 s34, s7, s28
	s_addc_u32 s35, s8, s29
	s_add_i32 s61, s11, 0
	s_add_i32 m0, s61, 0x10000
	s_mul_i32 s30, s50, s73
	global_load_lds_dwordx4 v132, s[34:35]
	s_add_i32 m0, s61, 0x12000
	s_add_u32 s28, s34, s44
	global_load_lds_dwordx4 v128, s[34:35]
	s_addc_u32 s29, s35, s45
	s_add_i32 m0, s61, 0x14000
	v_mov_b32_e32 v133, v209
	global_load_lds_dwordx4 v132, s[28:29]
	s_add_i32 m0, s61, 0x16000
	s_add_u32 s30, s74, s30
	s_addc_u32 s31, s75, s31
	s_add_i32 s62, s61, 0x2000
	global_load_lds_dwordx4 v128, s[28:29]
	s_mov_b32 m0, s61
	s_add_u32 s52, s30, s44
	global_load_lds_dwordx4 v134, s[30:31]
	s_mov_b32 m0, s62
	s_addc_u32 s53, s31, s45
	s_add_i32 s63, s61, 0x4000
	global_load_lds_dwordx4 v130, s[30:31]
	s_mov_b32 m0, s63
	s_add_i32 s64, s61, 0x6000
	global_load_lds_dwordx4 v134, s[52:53]
	s_mov_b32 m0, s64
	v_mov_b32_e32 v129, v209
	global_load_lds_dwordx4 v130, s[52:53]
	v_mov_b32_e32 v135, v209
	v_mov_b32_e32 v131, v209
	s_cmp_eq_u32 s39, 1
	v_lshl_add_u64 v[8:9], s[34:35], 0, v[132:133]
	v_lshl_add_u64 v[4:5], s[34:35], 0, v[128:129]
	v_lshl_add_u64 v[2:3], s[28:29], 0, v[132:133]
	v_lshl_add_u64 v[0:1], s[28:29], 0, v[128:129]
	v_lshl_add_u64 v[6:7], s[30:31], 0, v[134:135]
	s_cselect_b64 s[28:29], -1, 0
	s_cmp_lg_u32 s39, 1
	v_lshl_add_u64 v[10:11], s[30:31], 0, v[130:131]
	s_cbranch_scc1 .LBB0_180
	s_barrier

; template <int NP> __device__ __forceinline__ void load_rstd8(const float* ss, const Unit& u, int wr, int fr, int fq, float inv_n, float (&rs)[2][4]) {
;     f32x4 v[2][4];
; #pragma unroll
;     for (int ai = 0; ai < 2; ++ai)
; #pragma unroll
;         for (int m = 0; m < 4; ++m) { const int row = u.pm * BM + ai * HALF + wr * 64 + m * 16 + fr; v[ai][m] = *(const f32x4*)(ss + (size_t)row * NP + (NP == 16 ? 4 * fq : 0)); }
; #pragma unroll
;     for (int ai = 0; ai < 2; ++ai)
; #pragma unroll
;         for (int m = 0; m < 4; ++m) { float t = (v[ai][m][0] + v[ai][m][1]) + (v[ai][m][2] + v[ai][m][3]); if (NP == 16) t = quad_sum(t); rs[ai][m] = __builtin_amdgcn_rsqf(t * inv_n + kEps); }
; }
.LBB0_194:
	s_lshl_b32 s34, s73, 8
	v_add_u32_e32 v162, s34, v147
	v_lshlrev_b32_e32 v170, 2, v238
	v_add_u32_e32 v170, 0x20000, v170
	ds_read_b32 v171, v170
	ds_read_b32 v164, v170 offset:2048
	ds_read_b32 v166, v170 offset:4096
	ds_read_b32 v160, v170 offset:6144
	ds_read_b32 v156, v170 offset:8192
	ds_read_b32 v154, v170 offset:10240
	ds_read_b32 v150, v170 offset:12288
	ds_read_b32 v158, v170 offset:14336
	ds_read_b32 v146, v170 offset:16384
	v_add_u32_e32 v152, 0x80, v162
	v_add_u32_e32 v148, 0x90, v162
	v_add_u32_e32 v144, 0xa0, v162
	v_add_u32_e32 v142, 0xb0, v162
	s_waitcnt lgkmcnt(0)
	v_cmp_eq_u32_e32 vcc, s73, v171
	s_nop 4
	s_cbranch_vccnz .Lgu_rs_hit
	v_ashrrev_i32_e32 v163, 31, v162
	v_or_b32_e32 v144, 16, v162
	v_lshlrev_b64 v[142:143], 6, v[162:163]
	v_ashrrev_i32_e32 v145, 31, v144
	v_lshl_add_u64 v[142:143], v[136:137], 0, v[142:143]
	v_lshlrev_b64 v[144:145], 6, v[144:145]
	v_lshl_add_u64 v[144:145], v[136:137], 0, v[144:145]
	global_load_dwordx4 v[164:167], v[142:143], off
	global_load_dwordx4 v[168:171], v[144:145], off
	v_or_b32_e32 v142, 32, v162
	v_ashrrev_i32_e32 v143, 31, v142
	v_or_b32_e32 v144, 48, v162
	v_lshlrev_b64 v[142:143], 6, v[142:143]
	v_ashrrev_i32_e32 v145, 31, v144
	v_add_u32_e32 v152, 0x80, v162
	v_lshl_add_u64 v[142:143], v[136:137], 0, v[142:143]
	v_lshlrev_b64 v[144:145], 6, v[144:145]
	v_ashrrev_i32_e32 v153, 31, v152
	v_lshl_add_u64 v[144:145], v[136:137], 0, v[144:145]
	global_load_dwordx4 v[172:175], v[142:143], off
	global_load_dwordx4 v[176:179], v[144:145], off
	v_lshlrev_b64 v[142:143], 6, v[152:153]
	v_lshl_add_u64 v[142:143], v[136:137], 0, v[142:143]
	global_load_dwordx4 v[180:183], v[142:143], off
	v_add_u32_e32 v148, 0x90, v162
	v_ashrrev_i32_e32 v149, 31, v148
	v_lshlrev_b64 v[142:143], 6, v[148:149]
	v_lshl_add_u64 v[142:143], v[136:137], 0, v[142:143]
	global_load_dwordx4 v[184:187], v[142:143], off
	v_add_u32_e32 v144, 0xa0, v162
	v_add_u32_e32 v142, 0xb0, v162
	v_ashrrev_i32_e32 v145, 31, v144
	v_ashrrev_i32_e32 v143, 31, v142
	v_lshlrev_b64 v[188:189], 6, v[144:145]
	v_lshlrev_b64 v[190:191], 6, v[142:143]
	v_lshl_add_u64 v[188:189], v[136:137], 0, v[188:189]
	v_lshl_add_u64 v[192:193], v[136:137], 0, v[190:191]
	global_load_dwordx4 v[188:191], v[188:189], off
	s_nop 0
	global_load_dwordx4 v[192:195], v[192:193], off
	s_waitcnt vmcnt(0)
	v_add_f32_e32 v143, v164, v165
	v_add_f32_e32 v145, v166, v167
	v_add_f32_e32 v143, v143, v145
	v_add_f32_e32 v145, v168, v169
	v_add_f32_e32 v146, v170, v171
	v_mov_b32_e32 v160, v143
	v_add_f32_e32 v145, v145, v146
	s_nop 0
	v_permlane16_swap_b32_e32 v143, v160
	v_add_f32_e32 v143, v143, v160
	v_add_f32_e32 v149, v172, v173
	v_add_f32_e32 v150, v174, v175
	v_add_f32_e32 v153, v176, v177
	v_add_f32_e32 v154, v178, v179
	v_add_f32_e32 v146, v149, v150
	v_add_f32_e32 v149, v153, v154
	v_mov_b32_e32 v153, v145
	v_add_f32_e32 v156, v180, v181
	v_add_f32_e32 v158, v182, v183
	v_permlane16_swap_b32_e32 v145, v153
	v_add_f32_e32 v150, v156, v158
	v_mov_b32_e32 v158, v143
	v_add_f32_e32 v145, v145, v153
	v_mov_b32_e32 v154, v146
	v_permlane32_swap_b32_e32 v143, v158
	v_mov_b32_e32 v153, v145
	v_permlane16_swap_b32_e32 v146, v154
	v_add_f32_e32 v143, v143, v158
	v_permlane32_swap_b32_e32 v145, v153
	v_add_f32_e32 v146, v146, v154
	v_fmamk_f32 v143, v143, 0x3a800000, v240
	v_add_f32_e32 v145, v145, v153
	v_mov_b32_e32 v154, v146
	v_rsq_f32_e32 v164, v143
	v_fmamk_f32 v143, v145, 0x3a800000, v240
	v_permlane32_swap_b32_e32 v146, v154
	v_rsq_f32_e32 v166, v143
	v_mov_b32_e32 v143, v150
	v_add_f32_e32 v146, v146, v154
	s_nop 0
	v_permlane16_swap_b32_e32 v150, v143
	v_mov_b32_e32 v156, v149
	v_fmamk_f32 v145, v146, 0x3a800000, v240
	v_add_f32_e32 v143, v150, v143
	v_permlane16_swap_b32_e32 v149, v156
	v_rsq_f32_e32 v160, v145
	v_mov_b32_e32 v145, v143
	v_add_f32_e32 v149, v149, v156
	s_nop 0
	v_permlane32_swap_b32_e32 v143, v145
	v_mov_b32_e32 v156, v149
	v_add_f32_e32 v143, v143, v145
	s_nop 0
	v_permlane32_swap_b32_e32 v149, v156
	v_fmamk_f32 v143, v143, 0x3a800000, v240
	v_add_f32_e32 v149, v149, v156
	v_rsq_f32_e32 v156, v143
	v_add_f32_e32 v143, v184, v185
	v_add_f32_e32 v145, v186, v187
	v_add_f32_e32 v143, v143, v145
	v_mov_b32_e32 v145, v143
	s_nop 1
	v_permlane16_swap_b32_e32 v143, v145
	v_add_f32_e32 v143, v143, v145
	v_mov_b32_e32 v145, v143
	s_nop 1
	v_permlane32_swap_b32_e32 v143, v145
	v_add_f32_e32 v143, v143, v145
	v_fmamk_f32 v143, v143, 0x3a800000, v240
	v_rsq_f32_e32 v154, v143
	v_add_f32_e32 v143, v188, v189
	v_add_f32_e32 v145, v190, v191
	v_add_f32_e32 v143, v143, v145
	v_mov_b32_e32 v145, v143
	s_nop 1
	v_permlane16_swap_b32_e32 v143, v145
	v_add_f32_e32 v143, v143, v145
	v_mov_b32_e32 v145, v143
	s_nop 1
	v_permlane32_swap_b32_e32 v143, v145
	v_add_f32_e32 v143, v143, v145
	v_fmamk_f32 v143, v143, 0x3a800000, v240
	v_rsq_f32_e32 v150, v143
	v_add_f32_e32 v143, v192, v193
	v_add_f32_e32 v145, v194, v195
	v_add_f32_e32 v143, v143, v145
	v_mov_b32_e32 v145, v143
	s_nop 1
	v_permlane16_swap_b32_e32 v143, v145
	v_add_f32_e32 v143, v143, v145
	v_mov_b32_e32 v145, v143
	s_nop 1
	v_permlane32_swap_b32_e32 v143, v145
	v_add_f32_e32 v143, v143, v145
	v_fmamk_f32 v146, v149, 0x3a800000, v240
	v_fmamk_f32 v143, v143, 0x3a800000, v240
	v_rsq_f32_e32 v158, v146
	v_rsq_f32_e32 v146, v143
	v_lshlrev_b32_e32 v170, 2, v238
	v_add_u32_e32 v170, 0x20000, v170
	v_mov_b32_e32 v171, s73
	ds_write_b32 v170, v171
	ds_write_b32 v170, v164 offset:2048
	ds_write_b32 v170, v166 offset:4096
	ds_write_b32 v170, v160 offset:6144
	ds_write_b32 v170, v156 offset:8192
	ds_write_b32 v170, v154 offset:10240
	ds_write_b32 v170, v150 offset:12288
	ds_write_b32 v170, v158 offset:14336
	ds_write_b32 v170, v146 offset:16384
; __device__ __forceinline__ u32x2 pack4(const f32x4 v) { u32x2 w; w.x = cvt_pk_bf16(v[0], v[1]); w.y = cvt_pk_bf16(v[2], v[3]); return w; }
;     __device__ __forceinline__ void operator()(const f32x4 (&acc)[2][2][4][2], const Unit& u, int wr, int wc, int fr, int fq) const {
;     ...
;                 const int row = u.pm * BM + ai * HALF + wr * 64 + m * 16 + fr;
;                 const float rs = rsv[ai][m];
;                 u32x2 w[2];
; #pragma unroll
;                 for (int n = 0; n < 2; ++n) {
;                     const f32x4 g = acc[ai][0][m][n] * rs, up = acc[ai][1][m][n] * rs; f32x4 o;
; #pragma unroll
;                     for (int j = 0; j < 4; ++j) { const float e = __builtin_amdgcn_exp2f(-g[j] * kLog2e); o[j] = g[j] * up[j] * __builtin_amdgcn_rcpf(1.0f + e); }
;                     w[n] = pack4(o);
;                 }
;                 *(u32x4_*)(H + (size_t)row * 2816 + u.pn * 128 + wc * 32 + fq * 8) = (u32x4_){w[0].x, w[0].y, w[1].x, w[1].y};
.Lgu_rs_hit:
	s_and_b64 vcc, exec, s[38:39]
	v_mov_b32_e32 v168, v120
	v_mov_b32_e32 v169, v124
	v_pk_mul_f32 v[168:169], v[168:169], v[164:165] op_sel_hi:[1,0]
	v_mul_f32_e32 v120, 0xbfb8aa3b, v168
	v_mov_b32_e32 v124, v121
	v_exp_f32_e32 v143, v120
	v_pk_mul_f32 v[120:121], v[124:125], v[164:165] op_sel_hi:[1,0]
	v_mul_f32_e32 v145, v168, v169
	v_mul_f32_e32 v124, 0xbfb8aa3b, v120
	v_exp_f32_e32 v124, v124
	v_add_f32_e32 v125, 1.0, v143
	v_rcp_f32_e32 v143, v125
	v_mov_b32_e32 v125, v126
	v_add_f32_e32 v124, 1.0, v124
	v_rcp_f32_e32 v149, v124
	v_mov_b32_e32 v124, v122
	v_pk_mul_f32 v[124:125], v[124:125], v[164:165] op_sel_hi:[1,0]
	v_mul_f32_e32 v120, v120, v121
	v_mul_f32_e32 v122, 0xbfb8aa3b, v124
	v_exp_f32_e32 v122, v122
	v_mul_f32_e32 v143, v145, v143
	v_mul_f32_e32 v145, v120, v149
	v_mov_b32_e32 v126, v123
	v_add_f32_e32 v120, 1.0, v122
	v_rcp_f32_e32 v122, v120
	v_pk_mul_f32 v[120:121], v[126:127], v[164:165] op_sel_hi:[1,0]
	v_mul_f32_e32 v124, v124, v125
	v_mul_f32_e32 v123, 0xbfb8aa3b, v120
	v_exp_f32_e32 v123, v123
	v_mul_f32_e32 v125, v120, v121
	v_mov_b32_e32 v121, v112
	v_mul_f32_e32 v124, v124, v122
	v_add_f32_e32 v120, 1.0, v123
	v_rcp_f32_e32 v126, v120
	v_mov_b32_e32 v120, v116
	v_pk_mul_f32 v[122:123], v[120:121], v[164:165] op_sel_hi:[1,0]
	v_cvt_pk_bf16_f32 v120, v143, v145
	v_mul_f32_e32 v116, v125, v126
	v_mul_f32_e32 v112, 0xbfb8aa3b, v122
	v_exp_f32_e32 v112, v112
	v_cvt_pk_bf16_f32 v121, v124, v116
	v_mul_f32_e32 v122, v122, v123
	v_add_f32_e32 v112, 1.0, v112
	v_rcp_f32_e32 v116, v112
	v_mov_b32_e32 v112, v117
	v_pk_mul_f32 v[112:113], v[112:113], v[164:165] op_sel_hi:[1,0]
	v_mul_f32_e32 v116, v122, v116
	v_mul_f32_e32 v117, 0xbfb8aa3b, v112
	v_exp_f32_e32 v117, v117
	v_mul_f32_e32 v122, v112, v113
	v_mov_b32_e32 v113, v114
	v_add_f32_e32 v112, 1.0, v117
	v_rcp_f32_e32 v117, v112
	v_mov_b32_e32 v112, v118
	v_pk_mul_f32 v[112:113], v[112:113], v[164:165] op_sel_hi:[1,0]
	v_mul_f32_e32 v117, v122, v117
	v_mul_f32_e32 v114, 0xbfb8aa3b, v112
	v_exp_f32_e32 v118, v114
	v_mov_b32_e32 v114, v119
	v_pk_mul_f32 v[114:115], v[114:115], v[164:165] op_sel_hi:[1,0]
	v_mul_f32_e32 v112, v112, v113
	v_mul_f32_e32 v119, 0xbfb8aa3b, v114
	v_exp_f32_e32 v119, v119
	v_add_f32_e32 v118, 1.0, v118
	v_rcp_f32_e32 v118, v118
	v_mul_f32_e32 v113, v114, v115
	v_add_f32_e32 v119, 1.0, v119
	v_rcp_f32_e32 v119, v119
	v_mul_f32_e32 v112, v112, v118
	v_cvt_pk_bf16_f32 v122, v116, v117
	v_mul_f32_e32 v113, v113, v119
	v_cvt_pk_bf16_f32 v123, v112, v113
	v_mov_b64_e32 v[112:113], s[90:91]
	v_mad_i64_i32 v[114:115], s[30:31], v162, s80, v[112:113]
	s_lshl_b32 s30, s72, 7
	s_ashr_i32 s31, s30, 31
	s_lshl_b64 s[30:31], s[30:31], 1
	v_lshl_add_u64 v[114:115], v[114:115], 0, s[30:31]
	v_lshl_add_u64 v[114:115], v[114:115], 0, s[18:19]
	v_lshl_add_u64 v[114:115], v[114:115], 0, v[208:209]
	global_store_dwordx4 v[114:115], v[120:123], off
	v_mov_b32_e32 v114, v108
	v_mov_b32_e32 v115, v104
	v_pk_mul_f32 v[114:115], v[114:115], v[166:167] op_sel_hi:[1,0]
	s_nop 0
	v_mul_f32_e32 v104, 0xbfb8aa3b, v114
	v_exp_f32_e32 v108, v104
	v_mov_b32_e32 v104, v109
	v_pk_mul_f32 v[104:105], v[104:105], v[166:167] op_sel_hi:[1,0]
	v_mul_f32_e32 v114, v114, v115
	v_mul_f32_e32 v109, 0xbfb8aa3b, v104
	v_exp_f32_e32 v109, v109
	v_add_f32_e32 v108, 1.0, v108
	v_rcp_f32_e32 v115, v108
	v_mul_f32_e32 v104, v104, v105
	v_add_f32_e32 v108, 1.0, v109
	v_rcp_f32_e32 v116, v108
	v_mov_b32_e32 v108, v110
	v_mov_b32_e32 v109, v106
	v_pk_mul_f32 v[108:109], v[108:109], v[166:167] op_sel_hi:[1,0]
	v_mul_f32_e32 v110, v114, v115
	v_mul_f32_e32 v106, 0xbfb8aa3b, v108
	v_exp_f32_e32 v106, v106
	v_mul_f32_e32 v114, v104, v116
	v_add_f32_e32 v104, 1.0, v106
	v_mov_b32_e32 v106, v111
	v_rcp_f32_e32 v115, v104
	v_pk_mul_f32 v[104:105], v[106:107], v[166:167] op_sel_hi:[1,0]
	v_mul_f32_e32 v107, v108, v109
	v_mul_f32_e32 v106, 0xbfb8aa3b, v104
	v_exp_f32_e32 v106, v106
	v_mul_f32_e32 v109, v104, v105
	v_mov_b32_e32 v105, v96
	v_mul_f32_e32 v108, v107, v115
	v_add_f32_e32 v104, 1.0, v106
	v_rcp_f32_e32 v111, v104
	v_mov_b32_e32 v104, v100
	v_pk_mul_f32 v[106:107], v[104:105], v[166:167] op_sel_hi:[1,0]
	v_cvt_pk_bf16_f32 v104, v110, v114
	v_mul_f32_e32 v100, v109, v111
	v_mul_f32_e32 v96, 0xbfb8aa3b, v106
	v_exp_f32_e32 v96, v96
	v_cvt_pk_bf16_f32 v105, v108, v100
	v_mul_f32_e32 v106, v106, v107
	v_add_f32_e32 v96, 1.0, v96
	v_rcp_f32_e32 v100, v96
	v_mov_b32_e32 v96, v101
	v_pk_mul_f32 v[96:97], v[96:97], v[166:167] op_sel_hi:[1,0]
	v_mul_f32_e32 v100, v106, v100
	v_mul_f32_e32 v101, 0xbfb8aa3b, v96
	v_exp_f32_e32 v101, v101
	v_mul_f32_e32 v106, v96, v97
	v_mov_b32_e32 v97, v98
	v_add_f32_e32 v96, 1.0, v101
	v_rcp_f32_e32 v101, v96
	v_mov_b32_e32 v96, v102
	v_pk_mul_f32 v[96:97], v[96:97], v[166:167] op_sel_hi:[1,0]
	v_mul_f32_e32 v101, v106, v101
	v_mul_f32_e32 v98, 0xbfb8aa3b, v96
	v_exp_f32_e32 v102, v98
	v_mov_b32_e32 v98, v103
	v_pk_mul_f32 v[98:99], v[98:99], v[166:167] op_sel_hi:[1,0]
	v_mul_f32_e32 v96, v96, v97
	v_mul_f32_e32 v103, 0xbfb8aa3b, v98
	v_exp_f32_e32 v103, v103
	v_add_f32_e32 v102, 1.0, v102
	v_rcp_f32_e32 v102, v102
	v_mul_f32_e32 v97, v98, v99
	v_add_f32_e32 v103, 1.0, v103
	v_rcp_f32_e32 v103, v103
	v_mul_f32_e32 v96, v96, v102
	v_cvt_pk_bf16_f32 v106, v100, v101
	v_mul_f32_e32 v97, v97, v103
	v_cvt_pk_bf16_f32 v107, v96, v97
	v_add_u32_e32 v96, s34, v155
	v_mad_i64_i32 v[96:97], s[72:73], v96, s80, v[112:113]
	v_lshl_add_u64 v[96:97], v[96:97], 0, s[30:31]
	v_lshl_add_u64 v[96:97], v[96:97], 0, s[18:19]
	v_lshl_add_u64 v[96:97], v[96:97], 0, v[208:209]
	global_store_dwordx4 v[96:97], v[104:107], off
	v_mov_b32_e32 v96, v92
	v_mov_b32_e32 v97, v88
; __device__ __forceinline__ u32x2 pack4(const f32x4 v) { u32x2 w; w.x = cvt_pk_bf16(v[0], v[1]); w.y = cvt_pk_bf16(v[2], v[3]); return w; }
;     __device__ __forceinline__ void operator()(const f32x4 (&acc)[2][2][4][2], const Unit& u, int wr, int wc, int fr, int fq) const {
;     ...
;                 const int row = u.pm * BM + ai * HALF + wr * 64 + m * 16 + fr;
;                 const float rs = rsv[ai][m];
;                 u32x2 w[2];
; #pragma unroll
;                 for (int n = 0; n < 2; ++n) {
;                     const f32x4 g = acc[ai][0][m][n] * rs, up = acc[ai][1][m][n] * rs; f32x4 o;
; #pragma unroll
;                     for (int j = 0; j < 4; ++j) { const float e = __builtin_amdgcn_exp2f(-g[j] * kLog2e); o[j] = g[j] * up[j] * __builtin_amdgcn_rcpf(1.0f + e); }
;                     w[n] = pack4(o);
;                 }
;                 *(u32x4_*)(H + (size_t)row * 2816 + u.pn * 128 + wc * 32 + fq * 8) = (u32x4_){w[0].x, w[0].y, w[1].x, w[1].y};
	v_pk_mul_f32 v[96:97], v[96:97], v[160:161] op_sel_hi:[1,0]
	s_nop 0
	v_mul_f32_e32 v88, 0xbfb8aa3b, v96
	v_exp_f32_e32 v92, v88
	v_mov_b32_e32 v88, v93
	v_pk_mul_f32 v[88:89], v[88:89], v[160:161] op_sel_hi:[1,0]
	v_mul_f32_e32 v96, v96, v97
	v_mul_f32_e32 v93, 0xbfb8aa3b, v88
	v_exp_f32_e32 v93, v93
	v_add_f32_e32 v92, 1.0, v92
	v_rcp_f32_e32 v97, v92
	v_mul_f32_e32 v88, v88, v89
	v_add_f32_e32 v92, 1.0, v93
	v_rcp_f32_e32 v98, v92
	v_mov_b32_e32 v92, v94
	v_mov_b32_e32 v93, v90
	v_pk_mul_f32 v[92:93], v[92:93], v[160:161] op_sel_hi:[1,0]
	v_mul_f32_e32 v94, v96, v97
	v_mul_f32_e32 v90, 0xbfb8aa3b, v92
	v_exp_f32_e32 v90, v90
	v_mul_f32_e32 v96, v88, v98
	v_add_f32_e32 v88, 1.0, v90
	v_mov_b32_e32 v90, v95
	v_rcp_f32_e32 v97, v88
	v_pk_mul_f32 v[88:89], v[90:91], v[160:161] op_sel_hi:[1,0]
	v_mul_f32_e32 v91, v92, v93
	v_mul_f32_e32 v90, 0xbfb8aa3b, v88
	v_exp_f32_e32 v90, v90
	v_mul_f32_e32 v93, v88, v89
	v_mov_b32_e32 v89, v80
	v_mul_f32_e32 v92, v91, v97
	v_add_f32_e32 v88, 1.0, v90
	v_rcp_f32_e32 v95, v88
	v_mov_b32_e32 v88, v84
	v_pk_mul_f32 v[90:91], v[88:89], v[160:161] op_sel_hi:[1,0]
	v_cvt_pk_bf16_f32 v88, v94, v96
	v_mul_f32_e32 v84, v93, v95
	v_mul_f32_e32 v80, 0xbfb8aa3b, v90
	v_exp_f32_e32 v80, v80
	v_cvt_pk_bf16_f32 v89, v92, v84
	v_mul_f32_e32 v90, v90, v91
	v_add_f32_e32 v80, 1.0, v80
	v_rcp_f32_e32 v84, v80
	v_mov_b32_e32 v80, v85
	v_pk_mul_f32 v[80:81], v[80:81], v[160:161] op_sel_hi:[1,0]
	v_mul_f32_e32 v84, v90, v84
	v_mul_f32_e32 v85, 0xbfb8aa3b, v80
	v_exp_f32_e32 v85, v85
	v_mul_f32_e32 v90, v80, v81
	v_mov_b32_e32 v81, v82
	v_add_f32_e32 v80, 1.0, v85
	v_rcp_f32_e32 v85, v80
	v_mov_b32_e32 v80, v86
	v_pk_mul_f32 v[80:81], v[80:81], v[160:161] op_sel_hi:[1,0]
	v_mul_f32_e32 v85, v90, v85
	v_mul_f32_e32 v82, 0xbfb8aa3b, v80
	v_exp_f32_e32 v86, v82
	v_mov_b32_e32 v82, v87
	v_pk_mul_f32 v[82:83], v[82:83], v[160:161] op_sel_hi:[1,0]
	v_mul_f32_e32 v80, v80, v81
	v_mul_f32_e32 v87, 0xbfb8aa3b, v82
	v_exp_f32_e32 v87, v87
	v_add_f32_e32 v86, 1.0, v86
	v_rcp_f32_e32 v86, v86
	v_mul_f32_e32 v81, v82, v83
	v_add_f32_e32 v87, 1.0, v87
	v_rcp_f32_e32 v87, v87
	v_mul_f32_e32 v80, v80, v86
	v_cvt_pk_bf16_f32 v90, v84, v85
	v_mul_f32_e32 v81, v81, v87
	v_cvt_pk_bf16_f32 v91, v80, v81
	v_add_u32_e32 v80, s34, v157
	v_mad_i64_i32 v[80:81], s[72:73], v80, s80, v[112:113]
	v_lshl_add_u64 v[80:81], v[80:81], 0, s[30:31]
	v_lshl_add_u64 v[80:81], v[80:81], 0, s[18:19]
	v_lshl_add_u64 v[80:81], v[80:81], 0, v[208:209]
	global_store_dwordx4 v[80:81], v[88:91], off
	v_mov_b32_e32 v80, v76
	v_mov_b32_e32 v81, v72
	v_pk_mul_f32 v[80:81], v[80:81], v[158:159] op_sel_hi:[1,0]
	s_nop 0
	v_mul_f32_e32 v72, 0xbfb8aa3b, v80
	v_exp_f32_e32 v76, v72
	v_mov_b32_e32 v72, v77
	v_pk_mul_f32 v[72:73], v[72:73], v[158:159] op_sel_hi:[1,0]
	v_mul_f32_e32 v80, v80, v81
	v_mul_f32_e32 v77, 0xbfb8aa3b, v72
	v_exp_f32_e32 v77, v77
	v_add_f32_e32 v76, 1.0, v76
	v_rcp_f32_e32 v81, v76
	v_mul_f32_e32 v72, v72, v73
	v_add_f32_e32 v76, 1.0, v77
	v_rcp_f32_e32 v82, v76
	v_mov_b32_e32 v76, v78
	v_mov_b32_e32 v77, v74
	v_pk_mul_f32 v[76:77], v[76:77], v[158:159] op_sel_hi:[1,0]
	v_mul_f32_e32 v78, v80, v81
	v_mul_f32_e32 v74, 0xbfb8aa3b, v76
	v_exp_f32_e32 v74, v74
	v_mul_f32_e32 v80, v72, v82
	v_add_f32_e32 v72, 1.0, v74
	v_mov_b32_e32 v74, v79
	v_rcp_f32_e32 v81, v72
	v_pk_mul_f32 v[72:73], v[74:75], v[158:159] op_sel_hi:[1,0]
	v_mul_f32_e32 v75, v76, v77
	v_mul_f32_e32 v74, 0xbfb8aa3b, v72
	v_exp_f32_e32 v74, v74
	v_mul_f32_e32 v77, v72, v73
	v_mov_b32_e32 v73, v64
	v_mul_f32_e32 v76, v75, v81
	v_add_f32_e32 v72, 1.0, v74
	v_rcp_f32_e32 v79, v72
	v_mov_b32_e32 v72, v68
	v_pk_mul_f32 v[74:75], v[72:73], v[158:159] op_sel_hi:[1,0]
	v_cvt_pk_bf16_f32 v72, v78, v80
	v_mul_f32_e32 v68, v77, v79
	v_mul_f32_e32 v64, 0xbfb8aa3b, v74
	v_exp_f32_e32 v64, v64
	v_cvt_pk_bf16_f32 v73, v76, v68
	v_mul_f32_e32 v74, v74, v75
	v_add_f32_e32 v64, 1.0, v64
	v_rcp_f32_e32 v68, v64
	v_mov_b32_e32 v64, v69
	v_pk_mul_f32 v[64:65], v[64:65], v[158:159] op_sel_hi:[1,0]
	v_mul_f32_e32 v68, v74, v68
	v_mul_f32_e32 v69, 0xbfb8aa3b, v64
	v_exp_f32_e32 v69, v69
	v_mul_f32_e32 v74, v64, v65
	v_mov_b32_e32 v65, v66
	v_add_f32_e32 v64, 1.0, v69
	v_rcp_f32_e32 v69, v64
	v_mov_b32_e32 v64, v70
	v_pk_mul_f32 v[64:65], v[64:65], v[158:159] op_sel_hi:[1,0]
	v_mul_f32_e32 v69, v74, v69
	v_mul_f32_e32 v66, 0xbfb8aa3b, v64
	v_exp_f32_e32 v70, v66
	v_mov_b32_e32 v66, v71
	v_pk_mul_f32 v[66:67], v[66:67], v[158:159] op_sel_hi:[1,0]
	v_mul_f32_e32 v64, v64, v65
	v_mul_f32_e32 v71, 0xbfb8aa3b, v66
	v_exp_f32_e32 v71, v71
	v_add_f32_e32 v70, 1.0, v70
	v_rcp_f32_e32 v70, v70
	v_mul_f32_e32 v65, v66, v67
	v_add_f32_e32 v71, 1.0, v71
	v_rcp_f32_e32 v71, v71
	v_mul_f32_e32 v64, v64, v70
	v_cvt_pk_bf16_f32 v74, v68, v69
	v_mul_f32_e32 v65, v65, v71
	v_cvt_pk_bf16_f32 v75, v64, v65
	v_add_u32_e32 v64, s34, v159
	v_mad_i64_i32 v[64:65], s[34:35], v64, s80, v[112:113]
	v_lshl_add_u64 v[64:65], v[64:65], 0, s[30:31]
	v_lshl_add_u64 v[64:65], v[64:65], 0, s[18:19]
	v_lshl_add_u64 v[64:65], v[64:65], 0, v[208:209]
	global_store_dwordx4 v[64:65], v[72:75], off
	v_mov_b32_e32 v64, v60
	v_mov_b32_e32 v65, v56
	v_pk_mul_f32 v[64:65], v[64:65], v[156:157] op_sel_hi:[1,0]
	s_nop 0
	v_mul_f32_e32 v56, 0xbfb8aa3b, v64
	v_exp_f32_e32 v60, v56
	v_mov_b32_e32 v56, v61
	v_pk_mul_f32 v[56:57], v[56:57], v[156:157] op_sel_hi:[1,0]
	v_mul_f32_e32 v64, v64, v65
	v_mul_f32_e32 v61, 0xbfb8aa3b, v56
	v_exp_f32_e32 v61, v61
	v_add_f32_e32 v60, 1.0, v60
	v_rcp_f32_e32 v65, v60
	v_mul_f32_e32 v56, v56, v57
	v_add_f32_e32 v60, 1.0, v61
	v_rcp_f32_e32 v66, v60
	v_mov_b32_e32 v60, v62
	v_mov_b32_e32 v61, v58
; __device__ __forceinline__ u32x2 pack4(const f32x4 v) { u32x2 w; w.x = cvt_pk_bf16(v[0], v[1]); w.y = cvt_pk_bf16(v[2], v[3]); return w; }
;     __device__ __forceinline__ void operator()(const f32x4 (&acc)[2][2][4][2], const Unit& u, int wr, int wc, int fr, int fq) const {
;     ...
;                 const int row = u.pm * BM + ai * HALF + wr * 64 + m * 16 + fr;
;                 const float rs = rsv[ai][m];
;                 u32x2 w[2];
; #pragma unroll
;                 for (int n = 0; n < 2; ++n) {
;                     const f32x4 g = acc[ai][0][m][n] * rs, up = acc[ai][1][m][n] * rs; f32x4 o;
; #pragma unroll
;                     for (int j = 0; j < 4; ++j) { const float e = __builtin_amdgcn_exp2f(-g[j] * kLog2e); o[j] = g[j] * up[j] * __builtin_amdgcn_rcpf(1.0f + e); }
;                     w[n] = pack4(o);
;                 }
;                 *(u32x4_*)(H + (size_t)row * 2816 + u.pn * 128 + wc * 32 + fq * 8) = (u32x4_){w[0].x, w[0].y, w[1].x, w[1].y};
	v_pk_mul_f32 v[60:61], v[60:61], v[156:157] op_sel_hi:[1,0]
	v_mul_f32_e32 v62, v64, v65
	v_mul_f32_e32 v58, 0xbfb8aa3b, v60
	v_exp_f32_e32 v58, v58
	v_mul_f32_e32 v64, v56, v66
	v_add_f32_e32 v56, 1.0, v58
	v_mov_b32_e32 v58, v63
	v_rcp_f32_e32 v65, v56
	v_pk_mul_f32 v[56:57], v[58:59], v[156:157] op_sel_hi:[1,0]
	v_mul_f32_e32 v59, v60, v61
	v_mul_f32_e32 v58, 0xbfb8aa3b, v56
	v_exp_f32_e32 v58, v58
	v_mul_f32_e32 v61, v56, v57
	v_mov_b32_e32 v57, v48
	v_mul_f32_e32 v60, v59, v65
	v_add_f32_e32 v56, 1.0, v58
	v_rcp_f32_e32 v63, v56
	v_mov_b32_e32 v56, v52
	v_pk_mul_f32 v[58:59], v[56:57], v[156:157] op_sel_hi:[1,0]
	v_cvt_pk_bf16_f32 v56, v62, v64
	v_mul_f32_e32 v52, v61, v63
	v_mul_f32_e32 v48, 0xbfb8aa3b, v58
	v_exp_f32_e32 v48, v48
	v_cvt_pk_bf16_f32 v57, v60, v52
	v_mul_f32_e32 v58, v58, v59
	v_add_f32_e32 v48, 1.0, v48
	v_rcp_f32_e32 v52, v48
	v_mov_b32_e32 v48, v53
	v_pk_mul_f32 v[48:49], v[48:49], v[156:157] op_sel_hi:[1,0]
	v_mul_f32_e32 v52, v58, v52
	v_mul_f32_e32 v53, 0xbfb8aa3b, v48
	v_exp_f32_e32 v53, v53
	v_mul_f32_e32 v58, v48, v49
	v_mov_b32_e32 v49, v50
	v_add_f32_e32 v48, 1.0, v53
	v_rcp_f32_e32 v53, v48
	v_mov_b32_e32 v48, v54
	v_pk_mul_f32 v[48:49], v[48:49], v[156:157] op_sel_hi:[1,0]
	v_mul_f32_e32 v53, v58, v53
	v_mul_f32_e32 v50, 0xbfb8aa3b, v48
	v_exp_f32_e32 v54, v50
	v_mov_b32_e32 v50, v55
	v_pk_mul_f32 v[50:51], v[50:51], v[156:157] op_sel_hi:[1,0]
	v_mul_f32_e32 v48, v48, v49
	v_mul_f32_e32 v55, 0xbfb8aa3b, v50
	v_exp_f32_e32 v55, v55
	v_add_f32_e32 v54, 1.0, v54
	v_rcp_f32_e32 v54, v54
	v_mul_f32_e32 v49, v50, v51
	v_add_f32_e32 v55, 1.0, v55
	v_rcp_f32_e32 v55, v55
	v_mul_f32_e32 v48, v48, v54
	v_cvt_pk_bf16_f32 v58, v52, v53
	v_mul_f32_e32 v49, v49, v55
	v_cvt_pk_bf16_f32 v59, v48, v49
	v_mad_i64_i32 v[48:49], s[34:35], v152, s80, v[112:113]
	v_lshl_add_u64 v[48:49], v[48:49], 0, s[30:31]
	v_lshl_add_u64 v[48:49], v[48:49], 0, s[18:19]
	v_lshl_add_u64 v[48:49], v[48:49], 0, v[208:209]
	global_store_dwordx4 v[48:49], v[56:59], off
	v_mov_b32_e32 v48, v44
	v_mov_b32_e32 v49, v40
	v_pk_mul_f32 v[48:49], v[48:49], v[154:155] op_sel_hi:[1,0]
	s_nop 0
	v_mul_f32_e32 v40, 0xbfb8aa3b, v48
	v_exp_f32_e32 v44, v40
	v_mov_b32_e32 v40, v45
	v_pk_mul_f32 v[40:41], v[40:41], v[154:155] op_sel_hi:[1,0]
	v_mul_f32_e32 v48, v48, v49
	v_mul_f32_e32 v45, 0xbfb8aa3b, v40
	v_exp_f32_e32 v45, v45
	v_add_f32_e32 v44, 1.0, v44
	v_rcp_f32_e32 v49, v44
	v_mul_f32_e32 v40, v40, v41
	v_add_f32_e32 v44, 1.0, v45
	v_rcp_f32_e32 v50, v44
	v_mov_b32_e32 v44, v46
	v_mov_b32_e32 v45, v42
	v_pk_mul_f32 v[44:45], v[44:45], v[154:155] op_sel_hi:[1,0]
	v_mul_f32_e32 v46, v48, v49
	v_mul_f32_e32 v42, 0xbfb8aa3b, v44
	v_exp_f32_e32 v42, v42
	v_mul_f32_e32 v48, v40, v50
	v_add_f32_e32 v40, 1.0, v42
	v_mov_b32_e32 v42, v47
	v_rcp_f32_e32 v49, v40
	v_pk_mul_f32 v[40:41], v[42:43], v[154:155] op_sel_hi:[1,0]
	v_mul_f32_e32 v43, v44, v45
	v_mul_f32_e32 v42, 0xbfb8aa3b, v40
	v_exp_f32_e32 v42, v42
	v_mul_f32_e32 v45, v40, v41
	v_mov_b32_e32 v41, v32
	v_mul_f32_e32 v44, v43, v49
	v_add_f32_e32 v40, 1.0, v42
	v_rcp_f32_e32 v47, v40
	v_mov_b32_e32 v40, v36
	v_pk_mul_f32 v[42:43], v[40:41], v[154:155] op_sel_hi:[1,0]
	v_cvt_pk_bf16_f32 v40, v46, v48
	v_mul_f32_e32 v36, v45, v47
	v_mul_f32_e32 v32, 0xbfb8aa3b, v42
	v_exp_f32_e32 v32, v32
	v_cvt_pk_bf16_f32 v41, v44, v36
	v_mul_f32_e32 v42, v42, v43
	v_add_f32_e32 v32, 1.0, v32
	v_rcp_f32_e32 v36, v32
	v_mov_b32_e32 v32, v37
	v_pk_mul_f32 v[32:33], v[32:33], v[154:155] op_sel_hi:[1,0]
	v_mul_f32_e32 v36, v42, v36
	v_mul_f32_e32 v37, 0xbfb8aa3b, v32
	v_exp_f32_e32 v37, v37
	v_mul_f32_e32 v42, v32, v33
	v_mov_b32_e32 v33, v34
	v_add_f32_e32 v32, 1.0, v37
	v_rcp_f32_e32 v37, v32
	v_mov_b32_e32 v32, v38
	v_pk_mul_f32 v[32:33], v[32:33], v[154:155] op_sel_hi:[1,0]
	v_mul_f32_e32 v37, v42, v37
	v_mul_f32_e32 v34, 0xbfb8aa3b, v32
	v_exp_f32_e32 v38, v34
	v_mov_b32_e32 v34, v39
	v_pk_mul_f32 v[34:35], v[34:35], v[154:155] op_sel_hi:[1,0]
	v_mul_f32_e32 v32, v32, v33
	v_mul_f32_e32 v39, 0xbfb8aa3b, v34
	v_exp_f32_e32 v39, v39
	v_add_f32_e32 v38, 1.0, v38
	v_rcp_f32_e32 v38, v38
	v_mul_f32_e32 v33, v34, v35
	v_add_f32_e32 v39, 1.0, v39
	v_rcp_f32_e32 v39, v39
	v_mul_f32_e32 v32, v32, v38
	v_cvt_pk_bf16_f32 v42, v36, v37
	v_mul_f32_e32 v33, v33, v39
	v_cvt_pk_bf16_f32 v43, v32, v33
	v_mad_i64_i32 v[32:33], s[34:35], v148, s80, v[112:113]
	v_lshl_add_u64 v[32:33], v[32:33], 0, s[30:31]
	v_lshl_add_u64 v[32:33], v[32:33], 0, s[18:19]
	v_lshl_add_u64 v[32:33], v[32:33], 0, v[208:209]
	global_store_dwordx4 v[32:33], v[40:43], off
	v_mov_b32_e32 v32, v28
	v_mov_b32_e32 v33, v24
	v_pk_mul_f32 v[32:33], v[32:33], v[150:151] op_sel_hi:[1,0]
	s_nop 0
	v_mul_f32_e32 v24, 0xbfb8aa3b, v32
	v_exp_f32_e32 v28, v24
	v_mov_b32_e32 v24, v29
	v_pk_mul_f32 v[24:25], v[24:25], v[150:151] op_sel_hi:[1,0]
; __device__ __forceinline__ u32x2 pack4(const f32x4 v) { u32x2 w; w.x = cvt_pk_bf16(v[0], v[1]); w.y = cvt_pk_bf16(v[2], v[3]); return w; }
; #define PG8_BAR __builtin_amdgcn_s_barrier()
;     __device__ __forceinline__ void operator()(const f32x4 (&acc)[2][2][4][2], const Unit& u, int wr, int wc, int fr, int fq) const {
;     ...
;                 const int row = u.pm * BM + ai * HALF + wr * 64 + m * 16 + fr;
;                 const float rs = rsv[ai][m];
;                 u32x2 w[2];
; #pragma unroll
;                 for (int n = 0; n < 2; ++n) {
;                     const f32x4 g = acc[ai][0][m][n] * rs, up = acc[ai][1][m][n] * rs; f32x4 o;
; #pragma unroll
;                     for (int j = 0; j < 4; ++j) { const float e = __builtin_amdgcn_exp2f(-g[j] * kLog2e); o[j] = g[j] * up[j] * __builtin_amdgcn_rcpf(1.0f + e); }
;                     w[n] = pack4(o);
;                 }
;                 *(u32x4_*)(H + (size_t)row * 2816 + u.pn * 128 + wc * 32 + fq * 8) = (u32x4_){w[0].x, w[0].y, w[1].x, w[1].y};
; template <class Epi, class Sched, bool ALIGN_EPI = false, bool SP2 = false>
; __device__ __forceinline__ void gemm_phase(PG8_LAS unsigned char* lds, const Gemm g, const Sched& S, const Epi& E) {
;     ...
;         if constexpr (!Epi::AFTER_DRAIN) { E(acc, cur, wr, wc, fr, fq); S.done(cur); }
;         if (!has_next) break;
; #pragma unroll
;         for (int a = 0; a < 2; ++a)
; #pragma unroll
;             for (int b = 0; b < 2; ++b)
; #pragma unroll
;                 for (int m = 0; m < 4; ++m)
; #pragma unroll
;                     for (int n = 0; n < 2; ++n) acc[a][b][m][n] = (f32x4){0.f, 0.f, 0.f, 0.f};
;         cur = nxt; cA = nA; cB = nB; ++ui;
;         if constexpr (ALIGN_EPI) { if (wr == 1) PG8_BAR; }
	v_mul_f32_e32 v32, v32, v33
	v_mul_f32_e32 v29, 0xbfb8aa3b, v24
	v_exp_f32_e32 v29, v29
	v_add_f32_e32 v28, 1.0, v28
	v_rcp_f32_e32 v33, v28
	v_mul_f32_e32 v24, v24, v25
	v_add_f32_e32 v28, 1.0, v29
	v_rcp_f32_e32 v34, v28
	v_mov_b32_e32 v28, v30
	v_mov_b32_e32 v29, v26
	v_pk_mul_f32 v[28:29], v[28:29], v[150:151] op_sel_hi:[1,0]
	v_mul_f32_e32 v30, v32, v33
	v_mul_f32_e32 v26, 0xbfb8aa3b, v28
	v_exp_f32_e32 v26, v26
	v_mul_f32_e32 v32, v24, v34
	v_add_f32_e32 v24, 1.0, v26
	v_mov_b32_e32 v26, v31
	v_rcp_f32_e32 v33, v24
	v_pk_mul_f32 v[24:25], v[26:27], v[150:151] op_sel_hi:[1,0]
	v_mul_f32_e32 v27, v28, v29
	v_mul_f32_e32 v26, 0xbfb8aa3b, v24
	v_exp_f32_e32 v26, v26
	v_mul_f32_e32 v29, v24, v25
	v_mov_b32_e32 v25, v16
	v_mul_f32_e32 v28, v27, v33
	v_add_f32_e32 v24, 1.0, v26
	v_rcp_f32_e32 v31, v24
	v_mov_b32_e32 v24, v20
	v_pk_mul_f32 v[26:27], v[24:25], v[150:151] op_sel_hi:[1,0]
	v_cvt_pk_bf16_f32 v24, v30, v32
	v_mul_f32_e32 v20, v29, v31
	v_mul_f32_e32 v16, 0xbfb8aa3b, v26
	v_exp_f32_e32 v16, v16
	v_cvt_pk_bf16_f32 v25, v28, v20
	v_mul_f32_e32 v26, v26, v27
	v_add_f32_e32 v16, 1.0, v16
	v_rcp_f32_e32 v20, v16
	v_mov_b32_e32 v16, v21
	v_pk_mul_f32 v[16:17], v[16:17], v[150:151] op_sel_hi:[1,0]
	v_mul_f32_e32 v20, v26, v20
	v_mul_f32_e32 v21, 0xbfb8aa3b, v16
	v_exp_f32_e32 v21, v21
	v_mul_f32_e32 v26, v16, v17
	v_mov_b32_e32 v17, v18
	v_add_f32_e32 v16, 1.0, v21
	v_rcp_f32_e32 v21, v16
	v_mov_b32_e32 v16, v22
	v_pk_mul_f32 v[16:17], v[16:17], v[150:151] op_sel_hi:[1,0]
	v_mul_f32_e32 v21, v26, v21
	v_mul_f32_e32 v18, 0xbfb8aa3b, v16
	v_exp_f32_e32 v22, v18
	v_mov_b32_e32 v18, v23
	v_pk_mul_f32 v[18:19], v[18:19], v[150:151] op_sel_hi:[1,0]
	v_mul_f32_e32 v16, v16, v17
	v_mul_f32_e32 v23, 0xbfb8aa3b, v18
	v_exp_f32_e32 v23, v23
	v_add_f32_e32 v22, 1.0, v22
	v_rcp_f32_e32 v22, v22
	v_mul_f32_e32 v17, v18, v19
	v_add_f32_e32 v23, 1.0, v23
	v_rcp_f32_e32 v23, v23
	v_mul_f32_e32 v16, v16, v22
	v_cvt_pk_bf16_f32 v26, v20, v21
	v_mul_f32_e32 v17, v17, v23
	v_cvt_pk_bf16_f32 v27, v16, v17
	v_mad_i64_i32 v[16:17], s[34:35], v144, s80, v[112:113]
	v_lshl_add_u64 v[16:17], v[16:17], 0, s[30:31]
	v_lshl_add_u64 v[16:17], v[16:17], 0, s[18:19]
	v_lshl_add_u64 v[16:17], v[16:17], 0, v[208:209]
	global_store_dwordx4 v[16:17], v[24:27], off
	v_mov_b32_e32 v16, v12
	v_mov_b32_e32 v17, v8
	v_pk_mul_f32 v[16:17], v[16:17], v[146:147] op_sel_hi:[1,0]
	s_nop 0
	v_mul_f32_e32 v8, 0xbfb8aa3b, v16
	v_exp_f32_e32 v12, v8
	v_mov_b32_e32 v8, v13
	v_pk_mul_f32 v[8:9], v[8:9], v[146:147] op_sel_hi:[1,0]
	v_mul_f32_e32 v16, v16, v17
	v_mul_f32_e32 v13, 0xbfb8aa3b, v8
	v_exp_f32_e32 v13, v13
	v_add_f32_e32 v12, 1.0, v12
	v_rcp_f32_e32 v17, v12
	v_mul_f32_e32 v8, v8, v9
	v_add_f32_e32 v12, 1.0, v13
	v_rcp_f32_e32 v18, v12
	v_mov_b32_e32 v12, v14
	v_mov_b32_e32 v13, v10
	v_pk_mul_f32 v[12:13], v[12:13], v[146:147] op_sel_hi:[1,0]
	v_mul_f32_e32 v14, v16, v17
	v_mul_f32_e32 v10, 0xbfb8aa3b, v12
	v_exp_f32_e32 v10, v10
	v_mul_f32_e32 v16, v8, v18
	v_add_f32_e32 v8, 1.0, v10
	v_mov_b32_e32 v10, v15
	v_rcp_f32_e32 v17, v8
	v_pk_mul_f32 v[8:9], v[10:11], v[146:147] op_sel_hi:[1,0]
	v_mul_f32_e32 v11, v12, v13
	v_mul_f32_e32 v10, 0xbfb8aa3b, v8
	v_exp_f32_e32 v10, v10
	v_mul_f32_e32 v13, v8, v9
	v_mov_b32_e32 v9, v0
	v_mul_f32_e32 v12, v11, v17
	v_add_f32_e32 v8, 1.0, v10
	v_rcp_f32_e32 v15, v8
	v_mov_b32_e32 v8, v4
	v_pk_mul_f32 v[10:11], v[8:9], v[146:147] op_sel_hi:[1,0]
	v_cvt_pk_bf16_f32 v8, v14, v16
	v_mul_f32_e32 v4, v13, v15
	v_mul_f32_e32 v0, 0xbfb8aa3b, v10
	v_exp_f32_e32 v0, v0
	v_cvt_pk_bf16_f32 v9, v12, v4
	v_mul_f32_e32 v10, v10, v11
	v_add_f32_e32 v0, 1.0, v0
	v_rcp_f32_e32 v4, v0
	v_mov_b32_e32 v0, v5
	v_pk_mul_f32 v[0:1], v[0:1], v[146:147] op_sel_hi:[1,0]
	v_mul_f32_e32 v4, v10, v4
	v_mul_f32_e32 v5, 0xbfb8aa3b, v0
	v_exp_f32_e32 v5, v5
	v_mul_f32_e32 v10, v0, v1
	v_mov_b32_e32 v1, v2
	v_add_f32_e32 v0, 1.0, v5
	v_rcp_f32_e32 v5, v0
	v_mov_b32_e32 v0, v6
	v_pk_mul_f32 v[0:1], v[0:1], v[146:147] op_sel_hi:[1,0]
	v_mul_f32_e32 v5, v10, v5
	v_mul_f32_e32 v2, 0xbfb8aa3b, v0
	v_exp_f32_e32 v6, v2
	v_mov_b32_e32 v2, v7
	v_pk_mul_f32 v[2:3], v[2:3], v[146:147] op_sel_hi:[1,0]
	v_mul_f32_e32 v0, v0, v1
	v_mul_f32_e32 v7, 0xbfb8aa3b, v2
	v_exp_f32_e32 v7, v7
	v_add_f32_e32 v6, 1.0, v6
	v_rcp_f32_e32 v6, v6
	v_mul_f32_e32 v1, v2, v3
	v_add_f32_e32 v7, 1.0, v7
	v_rcp_f32_e32 v7, v7
	v_mul_f32_e32 v0, v0, v6
	v_cvt_pk_bf16_f32 v10, v4, v5
	v_mul_f32_e32 v1, v1, v7
	v_cvt_pk_bf16_f32 v11, v0, v1
	v_mad_i64_i32 v[0:1], s[34:35], v142, s80, v[112:113]
	v_lshl_add_u64 v[0:1], v[0:1], 0, s[30:31]
	v_lshl_add_u64 v[0:1], v[0:1], 0, s[18:19]
	v_lshl_add_u64 v[0:1], v[0:1], 0, v[208:209]
	s_mov_b64 s[30:31], -1
	global_store_dwordx4 v[0:1], v[8:11], off
	s_cbranch_vccnz .LBB0_182
	s_andn2_b64 vcc, exec, s[28:29]
	s_cbranch_vccnz .LBB0_181
	s_barrier
	s_branch .LBB0_181
